# stack: static third queue item + redundant queue/item barriers removed, on top of the XCD-aware attention raster
# baseline (speedup 1.0000x reference)
.LBB0_544:
	s_and_saveexec_b64 s[0:1], s[14:15]
	s_cbranch_execz .LBB0_548
	v_cmp_le_i32_e32 vcc, 0, v255
	s_cbranch_vccnz .Lar_static
	v_mov_b32_e32 v255, 1
	global_atomic_add v255, v3, v255, s[66:67] sc0
	s_waitcnt vmcnt(0)
	v_cmp_le_u32_e32 vcc, 64, v255
	v_add_u32_e32 v0, 0x400, v255
	v_add_u32_e32 v1, 0x600, v255
	v_cndmask_b32_e32 v0, v0, v1, vcc
	v_mov_b32_e32 v255, -1
	s_branch .Lar_have
